# norm phases: hoist per-row norm-weight loads out of the row loop (removes 7-15 serialized load+wait per row)
# speedup vs baseline: 1.0050x; 1.0050x over previous
; __device__ __forceinline__ unsigned pk2(float lo, float hi) { unsigned r; asm("v_cvt_pk_bf16_f32 %0, %1, %2" : "=v"(r) : "v"(lo), "v"(hi)); return r; }
; __device__ __forceinline__ void row_load(const float* p, int lane, f32x4 (&v)[8]) {
; #pragma unroll
;     for (int j = 0; j < 8; ++j) v[j] = *(const f32x4*)(p + 4 * lane + 256 * j);
; }
; __device__ __forceinline__ float row_rstd(const f32x4 (&v)[8]) {
;     float s = 0.f;
; #pragma unroll
;     for (int j = 0; j < 8; ++j) s += (v[j][0] * v[j][0] + v[j][1] * v[j][1]) + (v[j][2] * v[j][2] + v[j][3] * v[j][3]);
;     return rsqrtf(wave_sum(s) * (1.f / DM) + EPSN);
; }
; __device__ __forceinline__ void row_store_bf16(bf16_t* o, int lane, const f32x4 (&v)[8], float rstd, const float* g) {
; #pragma unroll
;     for (int j = 0; j < 8; ++j) { const f32x4 gg = *(const f32x4*)(g + 4 * lane + 256 * j);
;         u32x2 w; w.x = pk2(v[j][0] * rstd * gg[0], v[j][1] * rstd * gg[1]); w.y = pk2(v[j][2] * rstd * gg[2], v[j][3] * rstd * gg[3]);
;         *(u32x2*)(o + 4 * lane + 256 * j) = w; }
; }
; __device__ __forceinline__ const float* layer_in_row(const Params& P, int l, int r) {
;     if (l == 0) return r < TP ? P.xp + (size_t)r * DM : P.xs + (size_t)(r - TP) * DM;
;     return (const float*)(P.ws + WS_X2) + (size_t)r * DM;
; }
; __device__ __forceinline__ void phase_norm_in(const Params& P, int gw, int NGW, int lane) {
;     bf16_t* H = (bf16_t*)(P.ws + WS_H);
;     for (int r = gw; r < MROWS; r += NGW) { f32x4 v[8]; row_load(layer_in_row(P, 0, r), lane, v); __builtin_amdgcn_sched_barrier(0); const float rs = row_rstd(v); row_store_bf16(H + (size_t)r * DM, lane, v, rs, P.g_mix_pre); }
.LBB0_24:
	s_or_b64 exec, exec, s[4:5]
	s_load_dwordx16 s[36:51], s[0:1], 0x0
	s_movk_i32 s0, 0x2080
	v_cmp_gt_i32_e32 vcc, s0, v3
	v_mbcnt_lo_u32_b32 v31, -1, 0
	s_waitcnt lgkmcnt(0)
	v_writelane_b32 v252, s36, 36
	s_nop 1
	v_writelane_b32 v252, s37, 37
	v_writelane_b32 v252, s38, 38
	v_writelane_b32 v252, s39, 39
	v_writelane_b32 v252, s40, 40
	v_writelane_b32 v252, s41, 41
	v_writelane_b32 v252, s42, 42
	v_writelane_b32 v252, s43, 43
	v_writelane_b32 v252, s44, 44
	v_writelane_b32 v252, s45, 45
	v_writelane_b32 v252, s46, 46
	v_writelane_b32 v252, s47, 47
	v_writelane_b32 v252, s48, 48
	v_writelane_b32 v252, s49, 49
	v_writelane_b32 v252, s50, 50
	v_writelane_b32 v252, s51, 51
	s_and_saveexec_b64 s[0:1], vcc
	v_readlane_b32 s56, v252, 16
	v_readlane_b32 s57, v252, 17
	v_readlane_b32 s58, v252, 18
	v_readlane_b32 s59, v252, 19
	v_readlane_b32 s60, v252, 20
	v_readlane_b32 s61, v252, 21
	v_readlane_b32 s62, v252, 22
	v_readlane_b32 s63, v252, 23
	v_readlane_b32 s64, v252, 24
	v_readlane_b32 s65, v252, 25
	v_readlane_b32 s66, v252, 26
	v_readlane_b32 s67, v252, 27
	v_readlane_b32 s68, v252, 28
	v_readlane_b32 s69, v252, 29
	v_readlane_b32 s70, v252, 30
	v_readlane_b32 s71, v252, 31
	s_cbranch_execz .LBB0_27
	v_mbcnt_hi_u32_b32 v3, -1, v31
	v_and_b32_e32 v5, 64, v3
	v_add_u32_e32 v5, 64, v5
	v_xor_b32_e32 v6, 1, v3
	v_cmp_lt_i32_e32 vcc, v6, v5
	v_readlane_b32 s36, v252, 36
	v_mov_b32_e32 v15, 0
	v_cndmask_b32_e32 v6, v3, v6, vcc
	v_lshlrev_b32_e32 v32, 2, v6
	v_xor_b32_e32 v6, 2, v3
	v_cmp_lt_i32_e32 vcc, v6, v5
	v_lshlrev_b32_e32 v14, 4, v28
	v_readlane_b32 s50, v252, 50
	v_cndmask_b32_e32 v6, v3, v6, vcc
	v_lshlrev_b32_e32 v33, 2, v6
	v_xor_b32_e32 v6, 4, v3
	v_cmp_lt_i32_e32 vcc, v6, v5
	v_readlane_b32 s51, v252, 51
	s_mov_b64 s[4:5], 0x1000
	v_cndmask_b32_e32 v6, v3, v6, vcc
	v_lshlrev_b32_e32 v34, 2, v6
	v_xor_b32_e32 v6, 8, v3
	v_cmp_lt_i32_e32 vcc, v6, v5
	v_lshl_add_u64 v[16:17], s[50:51], 0, v[14:15]
	v_lshl_add_u64 v[18:19], v[16:17], 0, s[4:5]
	v_cndmask_b32_e32 v6, v3, v6, vcc
	v_lshlrev_b32_e32 v35, 2, v6
	v_xor_b32_e32 v6, 16, v3
	v_cmp_lt_i32_e32 vcc, v6, v5
	s_mov_b64 s[4:5], 0x1400
	v_lshl_add_u64 v[20:21], v[16:17], 0, s[4:5]
	v_cndmask_b32_e32 v6, v3, v6, vcc
	v_lshlrev_b32_e32 v36, 2, v6
	v_xor_b32_e32 v6, 32, v3
	s_mov_b64 s[4:5], 0x1800
	v_cmp_lt_i32_e32 vcc, v6, v5
	v_lshl_add_u64 v[22:23], v[16:17], 0, s[4:5]
	s_mov_b64 s[4:5], 0x1c00
	v_cndmask_b32_e32 v3, v3, v6, vcc
	v_lshl_add_u64 v[24:25], v[16:17], 0, s[4:5]
	v_readlane_b32 s4, v252, 32
	v_lshlrev_b32_e32 v37, 2, v3
	v_ashrrev_i32_e32 v3, 31, v2
	s_mov_b32 s6, s4
	s_ashr_i32 s7, s4, 31
	v_lshl_add_u64 v[26:27], v[2:3], 0, s[6:7]
	v_readlane_b32 s5, v252, 33
	v_lshlrev_b64 v[2:3], 12, v[26:27]
	v_readlane_b32 s37, v252, 37
	v_readlane_b32 s38, v252, 38
	v_readlane_b32 s39, v252, 39
	v_readlane_b32 s40, v252, 40
	v_readlane_b32 s41, v252, 41
	v_readlane_b32 s42, v252, 42
	v_readlane_b32 s43, v252, 43
	v_readlane_b32 s44, v252, 44
	v_readlane_b32 s45, v252, 45
	v_readlane_b32 s46, v252, 46
	v_readlane_b32 s47, v252, 47
	v_readlane_b32 s48, v252, 48
	v_readlane_b32 s49, v252, 49
	v_writelane_b32 v252, s4, 32
	v_lshl_or_b32 v2, v28, 3, v2
	v_lshlrev_b32_e32 v4, 2, v28
	v_writelane_b32 v252, s5, 33
	s_ashr_i32 s75, s74, 31
	v_lshl_add_u64 v[2:3], s[94:95], 0, v[2:3]
	s_mov_b64 s[4:5], 0x5800800
	v_lshl_add_u64 v[28:29], v[2:3], 0, s[4:5]
	s_lshl_b64 s[4:5], s[74:75], 12
	s_mov_b64 s[6:7], 0
	s_movk_i32 s8, 0x2000
	v_mov_b32_e32 v38, s39
	v_mov_b32_e32 v39, s37
	v_mov_b32_e32 v40, s38
	v_mov_b32_e32 v41, s36
	v_lshlrev_b32_e32 v14, 2, v4
	s_movk_i32 s9, 0x1000
	v_mov_b32_e32 v42, 0x358637bd
	s_mov_b32 s12, 0x800000
	s_movk_i32 s13, 0x207f
	global_load_dwordx4 v[140:143], v[16:17], off
	global_load_dwordx4 v[144:147], v[16:17], off offset:1024
	global_load_dwordx4 v[148:151], v[16:17], off offset:2048
	global_load_dwordx4 v[152:155], v[16:17], off offset:3072
	global_load_dwordx4 v[156:159], v[18:19], off
	global_load_dwordx4 v[160:163], v[20:21], off
	global_load_dwordx4 v[164:167], v[22:23], off
	global_load_dwordx4 v[168:171], v[24:25], off
.LBB0_26:
	v_add_u32_e32 v2, 0xffffe000, v26
	v_cmp_gt_i32_e32 vcc, s8, v26
	s_nop 1
	v_cndmask_b32_e32 v3, 0, v27, vcc
	v_cndmask_b32_e32 v2, v2, v26, vcc
	v_cndmask_b32_e32 v5, v38, v39, vcc
	v_cndmask_b32_e32 v4, v40, v41, vcc
	v_lshlrev_b64 v[2:3], 13, v[2:3]
	v_lshl_add_u64 v[2:3], v[4:5], 0, v[2:3]
	v_lshl_add_u64 v[2:3], v[2:3], 0, v[14:15]
	global_load_dwordx4 v[44:47], v[2:3], off
	global_load_dwordx4 v[48:51], v[2:3], off offset:1024
	global_load_dwordx4 v[52:55], v[2:3], off offset:2048
	global_load_dwordx4 v[56:59], v[2:3], off offset:3072
	v_add_co_u32_e32 v2, vcc, s9, v2
	s_nop 1
	v_addc_co_u32_e32 v3, vcc, 0, v3, vcc
	global_load_dwordx4 v[60:63], v[2:3], off
	global_load_dwordx4 v[10:13], v[2:3], off offset:1024
	global_load_dwordx4 v[6:9], v[2:3], off offset:2048
	s_nop 0
	global_load_dwordx4 v[2:5], v[2:3], off offset:3072
	s_nop 0
	s_waitcnt vmcnt(7)
	v_mov_b32_e32 v70, v45
	s_waitcnt vmcnt(6)
	v_mov_b32_e32 v71, v49
	v_mov_b32_e32 v74, v47
	v_mov_b32_e32 v75, v51
	v_mov_b32_e32 v68, v44
	v_mov_b32_e32 v69, v48
	v_mov_b32_e32 v72, v46
	v_mov_b32_e32 v73, v50
	s_waitcnt vmcnt(5)
	v_pk_mul_f32 v[76:77], v[54:55], v[54:55]
	v_pk_mul_f32 v[78:79], v[52:53], v[52:53]
	v_pk_mul_f32 v[70:71], v[70:71], v[70:71]
	v_pk_mul_f32 v[74:75], v[74:75], v[74:75]
	v_pk_mov_b32 v[92:93], v[78:79], v[76:77] op_sel:[1,0]
	v_mov_b32_e32 v79, v77
	v_pk_fma_f32 v[68:69], v[68:69], v[68:69], v[70:71]
	v_pk_fma_f32 v[70:71], v[72:73], v[72:73], v[74:75]
	s_waitcnt vmcnt(4)
; __device__ __forceinline__ unsigned pk2(float lo, float hi) { unsigned r; asm("v_cvt_pk_bf16_f32 %0, %1, %2" : "=v"(r) : "v"(lo), "v"(hi)); return r; }
; __device__ __forceinline__ float row_rstd(const f32x4 (&v)[8]) {
;     float s = 0.f;
; #pragma unroll
;     for (int j = 0; j < 8; ++j) s += (v[j][0] * v[j][0] + v[j][1] * v[j][1]) + (v[j][2] * v[j][2] + v[j][3] * v[j][3]);
;     return rsqrtf(wave_sum(s) * (1.f / DM) + EPSN);
; }
; __device__ __forceinline__ void row_store_bf16(bf16_t* o, int lane, const f32x4 (&v)[8], float rstd, const float* g) {
; #pragma unroll
;     for (int j = 0; j < 8; ++j) { const f32x4 gg = *(const f32x4*)(g + 4 * lane + 256 * j);
;         u32x2 w; w.x = pk2(v[j][0] * rstd * gg[0], v[j][1] * rstd * gg[1]); w.y = pk2(v[j][2] * rstd * gg[2], v[j][3] * rstd * gg[3]);
;         *(u32x2*)(o + 4 * lane + 256 * j) = w; }
; }
	v_mul_f32_e32 v80, v57, v57
	v_mul_f32_e32 v82, v59, v59
	v_pk_add_f32 v[72:73], v[92:93], v[78:79]
	v_pk_add_f32 v[68:69], v[68:69], v[70:71]
	s_waitcnt vmcnt(3)
	v_mul_f32_e32 v43, v60, v60
	v_mul_f32_e32 v91, v61, v61
	v_mul_f32_e32 v94, v62, v62
	v_mul_f32_e32 v95, v63, v63
	v_pk_fma_f32 v[76:77], v[56:57], v[56:57], v[80:81] op_sel_hi:[1,1,0]
	v_pk_fma_f32 v[80:81], v[58:59], v[58:59], v[82:83] op_sel_hi:[1,1,0]
	v_pk_add_f32 v[70:71], v[72:73], v[72:73] op_sel:[0,1] op_sel_hi:[1,0]
	v_pk_add_f32 v[68:69], v[68:69], v[68:69] op_sel:[0,1] op_sel_hi:[1,0]
	s_waitcnt vmcnt(2)
	v_pk_mul_f32 v[84:85], v[12:13], v[12:13]
	v_pk_mul_f32 v[86:87], v[10:11], v[10:11]
	v_mov_b32_e32 v77, v94
	v_mov_b32_e32 v81, v95
	v_mov_b32_e32 v71, v91
	v_mov_b32_e32 v69, v43
	v_pk_mov_b32 v[82:83], v[86:87], v[84:85] op_sel:[1,0]
	v_mov_b32_e32 v87, v85
	v_pk_add_f32 v[72:73], v[76:77], v[80:81]
	v_pk_add_f32 v[68:69], v[68:69], v[70:71]
	s_waitcnt vmcnt(1)
	v_mul_f32_e32 v88, v7, v7
	v_mul_f32_e32 v90, v9, v9
	v_pk_add_f32 v[74:75], v[82:83], v[86:87]
	v_pk_add_f32 v[68:69], v[68:69], v[72:73]
	s_waitcnt vmcnt(0)
	v_mul_f32_e32 v96, v2, v2
	v_mul_f32_e32 v97, v3, v3
	v_mul_f32_e32 v98, v4, v4
	v_mul_f32_e32 v99, v5, v5
	v_pk_fma_f32 v[84:85], v[6:7], v[6:7], v[88:89] op_sel_hi:[1,1,0]
	v_pk_fma_f32 v[88:89], v[8:9], v[8:9], v[90:91] op_sel_hi:[1,1,0]
	v_pk_add_f32 v[74:75], v[74:75], v[74:75] op_sel:[0,1] op_sel_hi:[1,0]
	v_pk_add_f32 v[68:69], v[68:69], v[68:69] op_sel:[0,1] op_sel_hi:[1,0]
	v_mov_b32_e32 v85, v98
	v_mov_b32_e32 v89, v99
	v_mov_b32_e32 v75, v97
	v_mov_b32_e32 v69, v96
	v_pk_add_f32 v[76:77], v[84:85], v[88:89]
	v_pk_add_f32 v[68:69], v[68:69], v[74:75]
	v_lshl_add_u64 v[26:27], v[26:27], 0, s[74:75]
	v_pk_add_f32 v[68:69], v[68:69], v[76:77]
	s_nop 0
	v_add_f32_e32 v43, v68, v69
	ds_bpermute_b32 v68, v32, v43
	s_waitcnt lgkmcnt(0)
	v_add_f32_e32 v43, v43, v68
	ds_bpermute_b32 v68, v33, v43
	s_waitcnt lgkmcnt(0)
	v_add_f32_e32 v43, v43, v68
	ds_bpermute_b32 v68, v34, v43
	s_waitcnt lgkmcnt(0)
	v_add_f32_e32 v43, v43, v68
	ds_bpermute_b32 v68, v35, v43
	s_waitcnt lgkmcnt(0)
	v_add_f32_e32 v43, v43, v68
	ds_bpermute_b32 v68, v36, v43
	s_waitcnt lgkmcnt(0)
	v_add_f32_e32 v43, v43, v68
	ds_bpermute_b32 v68, v37, v43
	s_waitcnt lgkmcnt(0)
	v_add_f32_e32 v43, v43, v68
	v_fmamk_f32 v43, v43, 0x3a000000, v42
	v_mul_f32_e32 v68, 0x4b800000, v43
	v_cmp_gt_f32_e32 vcc, s12, v43
	s_nop 1
	v_cndmask_b32_e32 v43, v43, v68, vcc
	v_rsq_f32_e32 v43, v43
	s_nop 0
	v_mul_f32_e32 v68, 0x45800000, v43
	v_cndmask_b32_e32 v43, v43, v68, vcc
	v_mul_f32_e32 v44, v44, v43
	v_mul_f32_e32 v45, v45, v43
	v_mul_f32_e32 v46, v46, v43
	v_mul_f32_e32 v47, v47, v43
	s_waitcnt vmcnt(0)
	v_mul_f32_e32 v44, v140, v44
	v_mul_f32_e32 v45, v141, v45
	v_mul_f32_e32 v46, v142, v46
	v_mul_f32_e32 v47, v143, v47
	v_cvt_pk_bf16_f32 v44, v44, v45
	v_cvt_pk_bf16_f32 v45, v46, v47
	global_store_dwordx2 v[28:29], v[44:45], off offset:-2048
	v_mul_f32_e32 v48, v48, v43
	v_mul_f32_e32 v49, v49, v43
	v_mul_f32_e32 v50, v50, v43
	v_mul_f32_e32 v51, v51, v43
	v_mul_f32_e32 v10, v10, v43
	v_mul_f32_e32 v11, v11, v43
	v_mul_f32_e32 v12, v12, v43
	v_mul_f32_e32 v13, v13, v43
	v_mul_f32_e32 v6, v6, v43
	v_mul_f32_e32 v7, v7, v43
	v_mul_f32_e32 v8, v8, v43
	v_mul_f32_e32 v9, v9, v43
	v_mul_f32_e32 v2, v2, v43
	v_mul_f32_e32 v3, v3, v43
	v_cmp_lt_i32_e32 vcc, s13, v26
	v_mul_f32_e32 v4, v4, v43
	v_mul_f32_e32 v5, v5, v43
	s_or_b64 s[6:7], vcc, s[6:7]
	v_mul_f32_e32 v44, v144, v48
	v_mul_f32_e32 v45, v145, v49
	v_mul_f32_e32 v46, v146, v50
	v_mul_f32_e32 v47, v147, v51
	v_cvt_pk_bf16_f32 v44, v44, v45
	v_cvt_pk_bf16_f32 v45, v46, v47
	global_store_dwordx2 v[28:29], v[44:45], off offset:-1536
	v_mul_f32_e32 v48, v52, v43
	v_mul_f32_e32 v49, v53, v43
	v_mul_f32_e32 v50, v54, v43
	v_mul_f32_e32 v51, v55, v43
	v_mul_f32_e32 v44, v148, v48
	v_mul_f32_e32 v45, v149, v49
	v_mul_f32_e32 v46, v150, v50
	v_mul_f32_e32 v47, v151, v51
	v_cvt_pk_bf16_f32 v44, v44, v45
	v_cvt_pk_bf16_f32 v45, v46, v47
	global_store_dwordx2 v[28:29], v[44:45], off offset:-1024
	v_mul_f32_e32 v48, v56, v43
	v_mul_f32_e32 v49, v57, v43
	v_mul_f32_e32 v50, v58, v43
	v_mul_f32_e32 v51, v59, v43
	v_mul_f32_e32 v44, v48, v152
	v_mul_f32_e32 v45, v49, v153
	v_mul_f32_e32 v46, v50, v154
	v_mul_f32_e32 v47, v51, v155
	v_cvt_pk_bf16_f32 v44, v44, v45
	v_cvt_pk_bf16_f32 v45, v46, v47
	global_store_dwordx2 v[28:29], v[44:45], off offset:-512
	v_mul_f32_e32 v48, v60, v43
	v_mul_f32_e32 v49, v61, v43
	v_mul_f32_e32 v50, v62, v43
	v_mul_f32_e32 v51, v63, v43
	v_mul_f32_e32 v44, v48, v156
	v_mul_f32_e32 v45, v49, v157
	v_mul_f32_e32 v46, v50, v158
	v_mul_f32_e32 v47, v51, v159
	v_cvt_pk_bf16_f32 v44, v44, v45
	v_cvt_pk_bf16_f32 v45, v46, v47
	global_store_dwordx2 v[28:29], v[44:45], off
	v_mul_f32_e32 v10, v10, v160
	v_mul_f32_e32 v11, v11, v161
	v_mul_f32_e32 v12, v12, v162
	v_mul_f32_e32 v13, v13, v163
	v_cvt_pk_bf16_f32 v10, v10, v11
	v_cvt_pk_bf16_f32 v11, v12, v13
	global_store_dwordx2 v[28:29], v[10:11], off offset:512
	v_mul_f32_e32 v6, v6, v164
	v_mul_f32_e32 v7, v7, v165
	v_mul_f32_e32 v8, v8, v166
	v_mul_f32_e32 v9, v9, v167
	v_cvt_pk_bf16_f32 v6, v6, v7
	v_cvt_pk_bf16_f32 v7, v8, v9
	global_store_dwordx2 v[28:29], v[6:7], off offset:1024
	v_mul_f32_e32 v2, v2, v168
	v_mul_f32_e32 v3, v3, v169
	v_mul_f32_e32 v4, v4, v170
	v_mul_f32_e32 v5, v5, v171
	v_cvt_pk_bf16_f32 v2, v2, v3
	v_cvt_pk_bf16_f32 v3, v4, v5
	global_store_dwordx2 v[28:29], v[2:3], off offset:1536
	v_lshl_add_u64 v[28:29], v[28:29], 0, s[4:5]
	s_andn2_b64 exec, exec, s[6:7]
	s_cbranch_execnz .LBB0_26

; __device__ __forceinline__ void phase_norm_mid(const Params& P, int l, int gw, int NGW, int lane) {
;     bf16_t* H = (bf16_t*)(P.ws + WS_H); const float* O = (const float*)(P.ws + WS_GATES); float* X1 = (float*)(P.ws + WS_X1);
;     const float* gp = P.g_mix_post + (size_t)l * DM;
;     for (int r = gw; r < MROWS; r += NGW) {
;         f32x4 o[8], x[8];
;         if (r < TP) row_load(O + (size_t)r * DM, lane, o);
;         else { const float* sr = (const float*)(P.ws + WS_SROW) + (size_t)(r - TP) * DM; row_load(sr, lane, o);
; #pragma unroll
;             for (int p = 1; p < 12; ++p) { f32x4 t[8]; row_load(sr + (size_t)p * 128 * DM, lane, t);
; #pragma unroll
;                 for (int j = 0; j < 8; ++j) o[j] = o[j] + t[j]; } }
;         row_load(layer_in_row(P, l, r), lane, x);
;         __builtin_amdgcn_sched_barrier(0);
;         const float rs = row_rstd(o);
; #pragma unroll
;         for (int j = 0; j < 8; ++j) { const f32x4 gg = *(const f32x4*)(gp + 4 * lane + 256 * j); x[j] = x[j] + o[j] * rs * gg; *(f32x4*)(X1 + (size_t)r * DM + 4 * lane + 256 * j) = x[j]; }
;         const float rs2 = row_rstd(x); row_store_bf16(H + (size_t)r * DM, lane, x, rs2, P.g_ffn_pre + (size_t)l * DM);
.LBB0_882:
	s_waitcnt lgkmcnt(0)
	s_barrier
	v_mbcnt_lo_u32_b32 v0, -1, 0
	v_mbcnt_hi_u32_b32 v0, -1, v0
	v_readlane_b32 s0, v252, 32
	v_or_b32_e32 v2, s85, v0
	v_readlane_b32 s1, v252, 33
	v_ashrrev_i32_e32 v0, 6, v2
	v_add_u32_e32 v1, s0, v0
	s_lshl_b32 s0, s96, 11
	s_mov_b32 s1, s83
	v_writelane_b32 v255, s0, 2
	s_nop 1
	v_writelane_b32 v255, s1, 3
	s_movk_i32 s0, 0x2080
	v_cmp_gt_i32_e32 vcc, s0, v1
	s_and_saveexec_b64 s[0:1], vcc
	s_cbranch_execz .LBB0_895
	v_lshlrev_b32_e32 v1, 2, v2
	v_and_b32_e32 v4, 0xfc, v1
	v_and_b32_e32 v1, 64, v246
	v_add_u32_e32 v1, 64, v1
	v_xor_b32_e32 v3, 1, v246
	v_cmp_lt_i32_e32 vcc, v3, v1
	v_readlane_b32 s2, v255, 2
	v_readlane_b32 s3, v255, 3
	v_cndmask_b32_e32 v3, v246, v3, vcc
	v_lshlrev_b32_e32 v100, 2, v3
	v_xor_b32_e32 v3, 2, v246
	v_cmp_lt_i32_e32 vcc, v3, v1
	s_lshl_b64 s[2:3], s[2:3], 2
	s_add_u32 s4, s56, s2
	v_cndmask_b32_e32 v3, v246, v3, vcc
	v_lshlrev_b32_e32 v101, 2, v3
	v_xor_b32_e32 v3, 4, v246
	v_cmp_lt_i32_e32 vcc, v3, v1
	s_addc_u32 s5, s57, s3
	v_lshlrev_b32_e32 v8, 2, v4
	v_cndmask_b32_e32 v3, v246, v3, vcc
	v_lshlrev_b32_e32 v102, 2, v3
	v_xor_b32_e32 v3, 8, v246
	v_cmp_lt_i32_e32 vcc, v3, v1
	s_add_u32 s2, s58, s2
	v_lshl_add_u64 v[50:51], s[4:5], 0, v[8:9]
	v_cndmask_b32_e32 v3, v246, v3, vcc
	v_lshlrev_b32_e32 v103, 2, v3
	v_xor_b32_e32 v3, 16, v246
	v_cmp_lt_i32_e32 vcc, v3, v1
	v_readlane_b32 s4, v254, 22
	s_addc_u32 s3, s59, s3
	v_cndmask_b32_e32 v3, v246, v3, vcc
	v_lshlrev_b32_e32 v104, 2, v3
	v_xor_b32_e32 v3, 32, v246
	v_cmp_lt_i32_e32 vcc, v3, v1
	v_readlane_b32 s5, v254, 23
	v_lshl_add_u64 v[66:67], s[2:3], 0, v[8:9]
	v_cndmask_b32_e32 v1, v246, v3, vcc
	v_readlane_b32 s2, v252, 32
	v_lshlrev_b32_e32 v105, 2, v1
	v_lshl_add_u64 v[52:53], s[4:5], 0, v[8:9]
	v_readlane_b32 s4, v252, 58
	v_ashrrev_i32_e32 v1, 31, v0
	v_readlane_b32 s3, v252, 33
	v_lshlrev_b32_e32 v6, 1, v4
	v_mov_b32_e32 v7, v9
	v_readlane_b32 s5, v252, 59
	v_lshl_add_u64 v[76:77], s[2:3], 0, v[0:1]
	v_lshlrev_b64 v[0:1], 13, v[76:77]
	v_lshl_add_u64 v[54:55], s[4:5], 0, v[6:7]
	v_readlane_b32 s4, v254, 34
	v_and_b32_e32 v2, 63, v2
	v_readlane_b32 s2, v252, 62
	s_mov_b64 s[8:9], 0x1000
	s_mov_b64 s[14:15], 0x1400
	s_mov_b64 s[18:19], 0x1800
	s_mov_b64 s[20:21], 0x1c00
	v_readlane_b32 s5, v254, 35
	v_lshl_or_b32 v0, v2, 4, v0
	v_readlane_b32 s3, v252, 63
	v_lshl_add_u64 v[56:57], v[50:51], 0, s[8:9]
	v_lshl_add_u64 v[58:59], v[50:51], 0, s[14:15]
	v_lshl_add_u64 v[60:61], v[50:51], 0, s[18:19]
	v_lshl_add_u64 v[62:63], v[50:51], 0, s[20:21]
	v_lshl_add_u64 v[64:65], s[4:5], 0, v[8:9]
	v_lshl_add_u64 v[68:69], v[66:67], 0, s[8:9]
	v_lshl_add_u64 v[70:71], v[66:67], 0, s[14:15]
	v_lshl_add_u64 v[72:73], v[66:67], 0, s[18:19]
	v_lshl_add_u64 v[74:75], v[66:67], 0, s[20:21]
	v_lshl_add_u64 v[78:79], s[2:3], 0, v[0:1]
	s_mov_b64 s[2:3], 0
	v_lshlrev_b32_e32 v8, 2, v4
	global_load_dwordx4 v[124:127], v[50:51], off
	global_load_dwordx4 v[128:131], v[50:51], off offset:1024
	global_load_dwordx4 v[132:135], v[50:51], off offset:2048
	global_load_dwordx4 v[136:139], v[50:51], off offset:3072
	global_load_dwordx4 v[140:143], v[56:57], off
	global_load_dwordx4 v[144:147], v[58:59], off
	global_load_dwordx4 v[148:151], v[60:61], off
	global_load_dwordx4 v[152:155], v[62:63], off
	global_load_dwordx4 v[156:159], v[66:67], off
	global_load_dwordx4 v[160:163], v[66:67], off offset:1024
	global_load_dwordx4 v[164:167], v[66:67], off offset:2048
	global_load_dwordx4 v[168:171], v[66:67], off offset:3072
	global_load_dwordx4 v[172:175], v[68:69], off
	global_load_dwordx4 v[176:179], v[70:71], off
	global_load_dwordx4 v[180:183], v[72:73], off
	global_load_dwordx4 v[184:187], v[74:75], off
	s_branch .LBB0_886

; __device__ __forceinline__ void phase_norm_mid(const Params& P, int l, int gw, int NGW, int lane) {
;     ...
;         row_load(layer_in_row(P, l, r), lane, x);
;         __builtin_amdgcn_sched_barrier(0);
;         const float rs = row_rstd(o);
; #pragma unroll
;         for (int j = 0; j < 8; ++j) { const f32x4 gg = *(const f32x4*)(gp + 4 * lane + 256 * j); x[j] = x[j] + o[j] * rs * gg; *(f32x4*)(X1 + (size_t)r * DM + 4 * lane + 256 * j) = x[j]; }
.LBB0_885:
	v_lshlrev_b64 v[34:35], 13, v[34:35]
	v_lshl_add_u64 v[34:35], v[36:37], 0, v[34:35]
	v_lshl_add_u64 v[34:35], v[34:35], 0, v[8:9]
	global_load_dwordx4 v[82:85], v[34:35], off
	global_load_dwordx4 v[86:89], v[34:35], off offset:1024
	global_load_dwordx4 v[90:93], v[34:35], off offset:2048
	global_load_dwordx4 v[94:97], v[34:35], off offset:3072
	v_add_co_u32_e32 v34, vcc, 0x1000, v34
	s_nop 1
	v_addc_co_u32_e32 v35, vcc, 0, v35, vcc
	global_load_dwordx4 v[46:49], v[34:35], off
	global_load_dwordx4 v[42:45], v[34:35], off offset:1024
	global_load_dwordx4 v[38:41], v[34:35], off offset:2048
	s_nop 0
	global_load_dwordx4 v[34:37], v[34:35], off offset:3072
	s_waitcnt vmcnt(15)
	v_pk_mul_f32 v[116:117], v[30:31], v[30:31]
	s_waitcnt vmcnt(14)
	v_pk_mul_f32 v[118:119], v[26:27], v[26:27]
	v_pk_mul_f32 v[106:107], v[32:33], v[32:33]
	v_pk_mul_f32 v[108:109], v[28:29], v[28:29]
	v_mov_b32_e32 v120, v116
	v_mov_b32_e32 v121, v118
	v_mov_b32_e32 v118, v117
	v_pk_add_f32 v[116:117], v[120:121], v[118:119]
	v_mov_b32_e32 v118, v106
	v_mov_b32_e32 v119, v108
	v_mov_b32_e32 v108, v107
	v_pk_add_f32 v[106:107], v[118:119], v[108:109]
	s_waitcnt vmcnt(13)
	v_pk_mul_f32 v[112:113], v[24:25], v[24:25]
	v_pk_add_f32 v[106:107], v[116:117], v[106:107]
	v_pk_mul_f32 v[114:115], v[22:23], v[22:23]
	v_pk_add_f32 v[116:117], v[106:107], v[106:107] op_sel_hi:[0,1]
	v_pk_mov_b32 v[118:119], v[114:115], v[112:113] op_sel:[1,0]
	v_mov_b32_e32 v115, v113
	v_pk_add_f32 v[112:113], v[118:119], v[114:115]
	s_waitcnt vmcnt(11)
	v_mul_f32_e32 v116, v17, v17
	v_pk_add_f32 v[112:113], v[112:113], v[112:113] op_sel_hi:[0,1]
	v_mul_f32_e32 v112, v18, v18
	v_pk_fma_f32 v[114:115], v[18:19], v[18:19], v[112:113] op_sel_hi:[1,1,0]
	v_mul_f32_e32 v112, v20, v20
	v_pk_fma_f32 v[118:119], v[20:21], v[20:21], v[112:113] op_sel_hi:[1,1,0]
	v_mul_f32_e32 v114, v14, v14
	v_mul_f32_e32 v118, v15, v15
	v_mul_f32_e32 v112, v16, v16
	s_waitcnt vmcnt(10)
	v_pk_mul_f32 v[98:99], v[12:13], v[12:13]
	v_pk_mul_f32 v[110:111], v[10:11], v[10:11]
	v_pk_add_f32 v[114:115], v[114:115], v[118:119]
	v_pk_add_f32 v[112:113], v[112:113], v[116:117]
	s_movk_i32 s4, 0x1000
	v_pk_add_f32 v[112:113], v[114:115], v[112:113]
	v_pk_mov_b32 v[114:115], v[110:111], v[98:99] op_sel:[1,0]
	v_mov_b32_e32 v111, v99
	v_pk_add_f32 v[98:99], v[114:115], v[110:111]
	v_pk_add_f32 v[112:113], v[112:113], v[112:113] op_sel_hi:[0,1]
	v_pk_add_f32 v[98:99], v[98:99], v[98:99] op_sel_hi:[0,1]
	s_waitcnt vmcnt(9)
	v_mul_f32_e32 v98, v4, v4
	v_pk_fma_f32 v[110:111], v[4:5], v[4:5], v[98:99] op_sel_hi:[1,1,0]
	v_mul_f32_e32 v98, v6, v6
	v_pk_fma_f32 v[114:115], v[6:7], v[6:7], v[98:99] op_sel_hi:[1,1,0]
	s_waitcnt vmcnt(8)
	v_mul_f32_e32 v110, v0, v0
	v_mul_f32_e32 v114, v1, v1
	v_mul_f32_e32 v98, v2, v2
	v_mul_f32_e32 v112, v3, v3
	v_pk_add_f32 v[110:111], v[110:111], v[114:115]
	v_pk_add_f32 v[98:99], v[98:99], v[112:113]
	v_lshl_add_u64 v[76:77], v[76:77], 0, s[74:75]
	v_pk_add_f32 v[98:99], v[110:111], v[98:99]
	s_nop 0
	v_add_f32_e32 v98, v98, v99
	ds_bpermute_b32 v99, v100, v98
	s_waitcnt lgkmcnt(0)
	v_add_f32_e32 v98, v98, v99
	ds_bpermute_b32 v99, v101, v98
	s_waitcnt lgkmcnt(0)
	v_add_f32_e32 v98, v98, v99
	ds_bpermute_b32 v99, v102, v98
	s_waitcnt lgkmcnt(0)
	v_add_f32_e32 v98, v98, v99
	ds_bpermute_b32 v99, v103, v98
	s_waitcnt lgkmcnt(0)
	v_add_f32_e32 v98, v98, v99
	ds_bpermute_b32 v99, v104, v98
	s_waitcnt lgkmcnt(0)
	v_add_f32_e32 v98, v98, v99
	ds_bpermute_b32 v99, v105, v98
	s_waitcnt lgkmcnt(0)
	v_add_f32_e32 v98, v98, v99
	v_fmamk_f32 v98, v98, 0x3a000000, v240
	v_mul_f32_e32 v99, 0x4b800000, v98
	v_cmp_gt_f32_e32 vcc, s72, v98
	s_nop 1
	v_cndmask_b32_e32 v98, v98, v99, vcc
	v_rsq_f32_e32 v110, v98
	v_lshlrev_b64 v[98:99], 13, v[80:81]
	v_lshl_add_u64 v[98:99], v[52:53], 0, v[98:99]
	v_mul_f32_e32 v111, 0x45800000, v110
	v_cndmask_b32_e32 v110, v110, v111, vcc
	v_pk_mul_f32 v[30:31], v[30:31], v[110:111] op_sel_hi:[1,0]
	v_pk_mul_f32 v[32:33], v[32:33], v[110:111] op_sel_hi:[1,0]
	s_waitcnt vmcnt(0)
	v_pk_fma_f32 v[30:31], v[124:125], v[30:31], v[82:83]
	v_pk_fma_f32 v[32:33], v[126:127], v[32:33], v[84:85]
	global_store_dwordx4 v[98:99], v[30:33], off
	v_pk_mul_f32 v[26:27], v[26:27], v[110:111] op_sel_hi:[1,0]
	v_pk_mul_f32 v[28:29], v[28:29], v[110:111] op_sel_hi:[1,0]
	v_pk_mul_f32 v[22:23], v[22:23], v[110:111] op_sel_hi:[1,0]
	v_pk_mul_f32 v[24:25], v[24:25], v[110:111] op_sel_hi:[1,0]
	v_pk_mul_f32 v[18:19], v[18:19], v[110:111] op_sel_hi:[1,0]
	v_pk_mul_f32 v[20:21], v[20:21], v[110:111] op_sel_hi:[1,0]
	v_pk_mul_f32 v[14:15], v[14:15], v[110:111] op_sel_hi:[1,0]
	v_pk_mul_f32 v[16:17], v[16:17], v[110:111] op_sel_hi:[1,0]
	v_pk_mul_f32 v[10:11], v[10:11], v[110:111] op_sel_hi:[1,0]
	v_pk_mul_f32 v[12:13], v[12:13], v[110:111] op_sel_hi:[1,0]
	v_pk_mul_f32 v[4:5], v[4:5], v[110:111] op_sel_hi:[1,0]
	v_pk_mul_f32 v[6:7], v[6:7], v[110:111] op_sel_hi:[1,0]
	v_pk_mul_f32 v[0:1], v[0:1], v[110:111] op_sel_hi:[1,0]
	v_pk_mul_f32 v[2:3], v[2:3], v[110:111] op_sel_hi:[1,0]
	v_pk_fma_f32 v[28:29], v[130:131], v[28:29], v[88:89]
	v_pk_fma_f32 v[26:27], v[128:129], v[26:27], v[86:87]
	global_store_dwordx4 v[98:99], v[26:29], off offset:1024
	v_add_co_u32_e32 v86, vcc, s4, v98
	s_movk_i32 s4, 0x207f
	s_nop 0
	v_addc_co_u32_e32 v87, vcc, 0, v99, vcc
	v_pk_fma_f32 v[24:25], v[134:135], v[24:25], v[92:93]
	v_pk_fma_f32 v[22:23], v[132:133], v[22:23], v[90:91]
	global_store_dwordx4 v[98:99], v[22:25], off offset:2048
	v_pk_fma_f32 v[20:21], v[138:139], v[20:21], v[96:97]
	v_pk_fma_f32 v[18:19], v[136:137], v[18:19], v[94:95]
	global_store_dwordx4 v[98:99], v[18:21], off offset:3072
; __device__ __forceinline__ unsigned pk2(float lo, float hi) { unsigned r; asm("v_cvt_pk_bf16_f32 %0, %1, %2" : "=v"(r) : "v"(lo), "v"(hi)); return r; }
; __device__ __forceinline__ void row_store_bf16(bf16_t* o, int lane, const f32x4 (&v)[8], float rstd, const float* g) {
; #pragma unroll
;     for (int j = 0; j < 8; ++j) { const f32x4 gg = *(const f32x4*)(g + 4 * lane + 256 * j);
;         u32x2 w; w.x = pk2(v[j][0] * rstd * gg[0], v[j][1] * rstd * gg[1]); w.y = pk2(v[j][2] * rstd * gg[2], v[j][3] * rstd * gg[3]);
;         *(u32x2*)(o + 4 * lane + 256 * j) = w; }
; }
; __device__ __forceinline__ void phase_norm_mid(const Params& P, int l, int gw, int NGW, int lane) {
;     ...
;         const float rs = row_rstd(o);
; #pragma unroll
;         for (int j = 0; j < 8; ++j) { const f32x4 gg = *(const f32x4*)(gp + 4 * lane + 256 * j); x[j] = x[j] + o[j] * rs * gg; *(f32x4*)(X1 + (size_t)r * DM + 4 * lane + 256 * j) = x[j]; }
;         const float rs2 = row_rstd(x); row_store_bf16(H + (size_t)r * DM, lane, x, rs2, P.g_ffn_pre + (size_t)l * DM);
	v_pk_fma_f32 v[16:17], v[142:143], v[16:17], v[48:49]
	v_pk_fma_f32 v[14:15], v[140:141], v[14:15], v[46:47]
	global_store_dwordx4 v[86:87], v[14:17], off
	v_pk_fma_f32 v[12:13], v[146:147], v[12:13], v[44:45]
	v_pk_fma_f32 v[10:11], v[144:145], v[10:11], v[42:43]
	global_store_dwordx4 v[86:87], v[10:13], off offset:1024
	v_mov_b32_e32 v48, v33
	v_mov_b32_e32 v49, v29
	v_mov_b32_e32 v46, v32
	v_mov_b32_e32 v47, v28
	v_pk_mul_f32 v[48:49], v[48:49], v[48:49]
	v_pk_fma_f32 v[6:7], v[6:7], v[150:151], v[40:41]
	v_pk_fma_f32 v[4:5], v[4:5], v[148:149], v[38:39]
	global_store_dwordx4 v[86:87], v[4:7], off offset:2048
	v_mov_b32_e32 v44, v31
	v_mov_b32_e32 v45, v27
	v_mov_b32_e32 v42, v30
	v_mov_b32_e32 v43, v26
	v_pk_mul_f32 v[44:45], v[44:45], v[44:45]
	v_pk_fma_f32 v[2:3], v[2:3], v[154:155], v[36:37]
	v_pk_fma_f32 v[0:1], v[0:1], v[152:153], v[34:35]
	global_store_dwordx4 v[86:87], v[0:3], off offset:3072
	v_pk_fma_f32 v[42:43], v[42:43], v[42:43], v[44:45]
	v_pk_fma_f32 v[44:45], v[46:47], v[46:47], v[48:49]
	v_pk_mul_f32 v[46:47], v[24:25], v[24:25]
	v_pk_add_f32 v[42:43], v[42:43], v[44:45]
	v_pk_mul_f32 v[44:45], v[22:23], v[22:23]
	v_pk_add_f32 v[42:43], v[42:43], v[42:43] op_sel_hi:[0,1]
	v_pk_mov_b32 v[48:49], v[44:45], v[46:47] op_sel:[1,0]
	v_mov_b32_e32 v45, v47
	v_pk_add_f32 v[44:45], v[48:49], v[44:45]
	v_mul_f32_e32 v42, v18, v18
	v_mul_f32_e32 v38, v20, v20
	v_pk_add_f32 v[44:45], v[44:45], v[44:45] op_sel_hi:[0,1]
	v_pk_fma_f32 v[40:41], v[18:19], v[18:19], v[42:43] op_sel_hi:[1,1,0]
	v_pk_fma_f32 v[38:39], v[20:21], v[20:21], v[38:39] op_sel_hi:[1,1,0]
	v_mul_f32_e32 v40, v14, v14
	v_mul_f32_e32 v38, v15, v15
	v_mul_f32_e32 v44, v16, v16
	v_mul_f32_e32 v42, v17, v17
	v_pk_add_f32 v[38:39], v[40:41], v[38:39]
	v_pk_add_f32 v[40:41], v[44:45], v[42:43]
	v_pk_mul_f32 v[42:43], v[12:13], v[12:13]
	v_pk_add_f32 v[38:39], v[38:39], v[40:41]
	v_pk_mul_f32 v[40:41], v[10:11], v[10:11]
	v_pk_add_f32 v[38:39], v[38:39], v[38:39] op_sel_hi:[0,1]
	v_pk_mov_b32 v[44:45], v[40:41], v[42:43] op_sel:[1,0]
	v_mov_b32_e32 v41, v43
	v_pk_add_f32 v[40:41], v[44:45], v[40:41]
	v_mul_f32_e32 v38, v4, v4
	v_pk_add_f32 v[40:41], v[40:41], v[40:41] op_sel_hi:[0,1]
	v_mul_f32_e32 v40, v6, v6
	v_pk_fma_f32 v[42:43], v[4:5], v[4:5], v[38:39] op_sel_hi:[1,1,0]
	v_pk_fma_f32 v[44:45], v[6:7], v[6:7], v[40:41] op_sel_hi:[1,1,0]
	v_mul_f32_e32 v42, v0, v0
	v_mul_f32_e32 v44, v1, v1
	v_mul_f32_e32 v40, v2, v2
	v_mul_f32_e32 v38, v3, v3
	v_pk_add_f32 v[42:43], v[42:43], v[44:45]
	v_pk_add_f32 v[38:39], v[40:41], v[38:39]
	s_nop 0
	v_pk_add_f32 v[38:39], v[42:43], v[38:39]
	s_nop 0
	v_add_f32_e32 v38, v38, v39
	ds_bpermute_b32 v39, v100, v38
	s_waitcnt lgkmcnt(0)
	v_add_f32_e32 v38, v38, v39
	ds_bpermute_b32 v39, v101, v38
	s_waitcnt lgkmcnt(0)
	v_add_f32_e32 v38, v38, v39
	ds_bpermute_b32 v39, v102, v38
	s_waitcnt lgkmcnt(0)
	v_add_f32_e32 v38, v38, v39
	ds_bpermute_b32 v39, v103, v38
	s_waitcnt lgkmcnt(0)
	v_add_f32_e32 v38, v38, v39
	ds_bpermute_b32 v39, v104, v38
	s_waitcnt lgkmcnt(0)
	v_add_f32_e32 v38, v38, v39
	ds_bpermute_b32 v39, v105, v38
	s_waitcnt lgkmcnt(0)
	v_add_f32_e32 v38, v38, v39
	v_fmamk_f32 v38, v38, 0x3a000000, v240
	v_mul_f32_e32 v39, 0x4b800000, v38
	v_cmp_gt_f32_e32 vcc, s72, v38
	s_nop 1
	v_cndmask_b32_e32 v38, v38, v39, vcc
	v_rsq_f32_e32 v40, v38
	v_lshlrev_b64 v[38:39], 12, v[80:81]
	v_lshl_add_u64 v[38:39], v[54:55], 0, v[38:39]
	v_mul_f32_e32 v41, 0x45800000, v40
	v_cndmask_b32_e32 v40, v40, v41, vcc
	v_mul_f32_e32 v30, v30, v40
	v_mul_f32_e32 v31, v31, v40
	v_mul_f32_e32 v32, v32, v40
	v_mul_f32_e32 v33, v33, v40
	v_mul_f32_e32 v30, v156, v30
	v_mul_f32_e32 v31, v157, v31
	v_mul_f32_e32 v32, v158, v32
	v_mul_f32_e32 v33, v159, v33
	v_cvt_pk_bf16_f32 v30, v30, v31
	v_cvt_pk_bf16_f32 v31, v32, v33
	global_store_dwordx2 v[38:39], v[30:31], off
	v_mul_f32_e32 v26, v26, v40
	v_mul_f32_e32 v27, v27, v40
	v_mul_f32_e32 v28, v28, v40
	v_mul_f32_e32 v29, v29, v40
	v_mul_f32_e32 v22, v22, v40
	v_mul_f32_e32 v23, v23, v40
	v_mul_f32_e32 v24, v24, v40
	v_mul_f32_e32 v25, v25, v40
	v_mul_f32_e32 v18, v18, v40
	v_mul_f32_e32 v19, v19, v40
	v_mul_f32_e32 v20, v20, v40
	v_mul_f32_e32 v21, v21, v40
	v_mul_f32_e32 v14, v14, v40
	v_mul_f32_e32 v15, v15, v40
	v_mul_f32_e32 v16, v16, v40
	v_mul_f32_e32 v17, v17, v40
	v_mul_f32_e32 v10, v10, v40
	v_mul_f32_e32 v11, v11, v40
	v_mul_f32_e32 v12, v12, v40
	v_mul_f32_e32 v13, v13, v40
	v_mul_f32_e32 v4, v4, v40
	v_mul_f32_e32 v5, v5, v40
	v_mul_f32_e32 v6, v6, v40
	v_mul_f32_e32 v7, v7, v40
	v_cmp_lt_i32_e32 vcc, s4, v76
	v_readlane_b32 s4, v254, 53
	v_mul_f32_e32 v0, v0, v40
	v_mul_f32_e32 v1, v1, v40
	v_readlane_b32 s5, v254, 54
	s_or_b64 s[2:3], vcc, s[2:3]
	v_mul_f32_e32 v2, v2, v40
	v_mul_f32_e32 v3, v3, v40
	v_lshl_add_u64 v[78:79], v[78:79], 0, s[4:5]
	v_mul_f32_e32 v26, v160, v26
	v_mul_f32_e32 v27, v161, v27
	v_mul_f32_e32 v28, v162, v28
	v_mul_f32_e32 v29, v163, v29
	v_cvt_pk_bf16_f32 v26, v26, v27
	v_cvt_pk_bf16_f32 v27, v28, v29
	global_store_dwordx2 v[38:39], v[26:27], off offset:512
	v_mul_f32_e32 v22, v164, v22
	v_mul_f32_e32 v23, v165, v23
	v_mul_f32_e32 v24, v166, v24
	v_mul_f32_e32 v25, v167, v25
	v_cvt_pk_bf16_f32 v22, v22, v23
	v_cvt_pk_bf16_f32 v23, v24, v25
	global_store_dwordx2 v[38:39], v[22:23], off offset:1024
	v_mul_f32_e32 v18, v168, v18
	v_mul_f32_e32 v19, v169, v19
	v_mul_f32_e32 v20, v170, v20
	v_mul_f32_e32 v21, v171, v21
	v_cvt_pk_bf16_f32 v18, v18, v19
	v_cvt_pk_bf16_f32 v19, v20, v21
	global_store_dwordx2 v[38:39], v[18:19], off offset:1536
	v_mul_f32_e32 v14, v14, v172
	v_mul_f32_e32 v15, v15, v173
	v_mul_f32_e32 v16, v16, v174
	v_mul_f32_e32 v17, v17, v175
	v_cvt_pk_bf16_f32 v14, v14, v15
	v_cvt_pk_bf16_f32 v15, v16, v17
	global_store_dwordx2 v[38:39], v[14:15], off offset:2048
	v_mul_f32_e32 v10, v10, v176
	v_mul_f32_e32 v11, v11, v177
	v_mul_f32_e32 v12, v12, v178
	v_mul_f32_e32 v13, v13, v179
	v_cvt_pk_bf16_f32 v10, v10, v11
	v_cvt_pk_bf16_f32 v11, v12, v13
	global_store_dwordx2 v[38:39], v[10:11], off offset:2560
	v_mul_f32_e32 v4, v4, v180
	v_mul_f32_e32 v5, v5, v181
	v_mul_f32_e32 v6, v6, v182
	v_mul_f32_e32 v7, v7, v183
	v_cvt_pk_bf16_f32 v4, v4, v5
	v_cvt_pk_bf16_f32 v5, v6, v7
	global_store_dwordx2 v[38:39], v[4:5], off offset:3072
	v_mul_f32_e32 v0, v0, v184
	v_mul_f32_e32 v1, v1, v185
	v_mul_f32_e32 v2, v2, v186
	v_mul_f32_e32 v3, v3, v187
	v_cvt_pk_bf16_f32 v0, v0, v1
	v_cvt_pk_bf16_f32 v1, v2, v3
	global_store_dwordx2 v[38:39], v[0:1], off offset:3584
	s_andn2_b64 exec, exec, s[2:3]
	s_cbranch_execz .LBB0_895

; __device__ __forceinline__ void phase_norm_out(const Params& P, int l, int gw, int NGW, int lane) {
;     bf16_t* H = (bf16_t*)(P.ws + WS_H); const float* F = (const float*)(P.ws + WS_GATES); const float* X1 = (const float*)(P.ws + WS_X1);
;     float* dst = (l == 0) ? (float*)(P.ws + WS_X2) : P.out;
;     const float* gp = P.g_ffn_post + (size_t)l * DM;
;     for (int r = gw; r < MROWS; r += NGW) {
;         f32x4 f[8], x[8];
;         if (r < TP) row_load(F + (size_t)r * DM, lane, f);
;         else { const float* sr = (const float*)(P.ws + WS_SROW) + (size_t)(r - TP) * DM; row_load(sr, lane, f);
; #pragma unroll
;             for (int p = 1; p < 11; ++p) { f32x4 t[8]; row_load(sr + (size_t)p * 128 * DM, lane, t);
; #pragma unroll
;                 for (int j = 0; j < 8; ++j) f[j] = f[j] + t[j]; } }
;         row_load(X1 + (size_t)r * DM, lane, x);
;         __builtin_amdgcn_sched_barrier(0);
;         const float rs = row_rstd(f);
; #pragma unroll
;         for (int j = 0; j < 8; ++j) { const f32x4 gg = *(const f32x4*)(gp + 4 * lane + 256 * j); x[j] = x[j] + f[j] * rs * gg; *(f32x4*)(dst + (size_t)r * DM + 4 * lane + 256 * j) = x[j]; }
;         if (l == 0) { const float rs2 = row_rstd(x); row_store_bf16(H + (size_t)r * DM, lane, x, rs2, P.g_mix_pre + DM); }
.LBB0_2096:
	s_waitcnt lgkmcnt(0)
	s_barrier
	v_mbcnt_lo_u32_b32 v0, -1, 0
	v_mbcnt_hi_u32_b32 v0, -1, v0
	v_readlane_b32 s0, v252, 32
	v_or_b32_e32 v104, s85, v0
	v_readlane_b32 s1, v252, 33
	v_ashrrev_i32_e32 v50, 6, v104
	v_add_u32_e32 v102, s0, v50
	s_movk_i32 s0, 0x2080
	v_and_b32_e32 v103, 63, v104
	v_cmp_gt_i32_e32 vcc, s0, v102
	s_and_saveexec_b64 s[0:1], vcc
	s_cbranch_execz .LBB0_2105
	v_and_b32_e32 v0, 64, v246
	v_add_u32_e32 v0, 64, v0
	v_xor_b32_e32 v1, 1, v246
	v_cmp_lt_i32_e32 vcc, v1, v0
	v_readlane_b32 s2, v255, 2
	v_readlane_b32 s3, v255, 3
	v_cndmask_b32_e32 v1, v246, v1, vcc
	v_lshlrev_b32_e32 v105, 2, v1
	v_xor_b32_e32 v1, 2, v246
	v_cmp_lt_i32_e32 vcc, v1, v0
	s_lshl_b64 s[2:3], s[2:3], 2
	s_add_u32 s2, s60, s2
	v_cndmask_b32_e32 v1, v246, v1, vcc
	v_lshlrev_b32_e32 v106, 2, v1
	v_xor_b32_e32 v1, 4, v246
	v_cmp_lt_i32_e32 vcc, v1, v0
	s_addc_u32 s3, s61, s3
	v_lshlrev_b32_e32 v8, 4, v103
	v_cndmask_b32_e32 v1, v246, v1, vcc
	v_lshlrev_b32_e32 v107, 2, v1
	v_xor_b32_e32 v1, 8, v246
	v_cmp_lt_i32_e32 vcc, v1, v0
	v_lshl_add_u64 v[54:55], s[2:3], 0, v[8:9]
	v_readlane_b32 s2, v252, 58
	v_cndmask_b32_e32 v1, v246, v1, vcc
	v_lshlrev_b32_e32 v108, 2, v1
	v_xor_b32_e32 v1, 16, v246
	v_cmp_lt_i32_e32 vcc, v1, v0
	v_readlane_b32 s3, v252, 59
	v_readlane_b32 s4, v254, 55
	v_cndmask_b32_e32 v1, v246, v1, vcc
	v_lshlrev_b32_e32 v109, 2, v1
	v_xor_b32_e32 v1, 32, v246
	v_cmp_lt_i32_e32 vcc, v1, v0
	v_readlane_b32 s5, v254, 56
	s_and_b64 s[4:5], s[4:5], exec
	v_cndmask_b32_e32 v0, v246, v1, vcc
	v_lshlrev_b32_e32 v110, 2, v0
	v_lshlrev_b32_e32 v0, 3, v103
	v_mov_b32_e32 v1, v9
	v_lshl_add_u64 v[58:59], s[2:3], 0, v[0:1]
	v_readlane_b32 s2, v254, 34
	v_readlane_b32 s3, v254, 35
	v_readlane_b32 s4, v254, 36
	v_ashrrev_i32_e32 v51, 31, v50
	v_lshl_add_u64 v[68:69], s[2:3], 0, v[8:9]
	v_readlane_b32 s2, v254, 46
	v_readlane_b32 s3, v254, 47
	v_readlane_b32 s5, v254, 37
	v_readlane_b32 s8, v254, 22
	v_lshl_add_u64 v[70:71], s[2:3], 0, v[8:9]
	v_readlane_b32 s2, v252, 32
	v_readlane_b32 s3, v252, 33
	s_cselect_b32 s5, s5, s93
	s_cselect_b32 s4, s4, s92
	v_lshl_add_u64 v[80:81], s[2:3], 0, v[50:51]
	v_readlane_b32 s9, v254, 23
	v_lshlrev_b64 v[0:1], 13, v[80:81]
	v_readlane_b32 s2, v252, 62
	v_lshl_add_u64 v[52:53], s[8:9], 0, v[8:9]
	v_lshl_add_u64 v[56:57], s[4:5], 0, v[8:9]
	s_mov_b64 s[4:5], 0x1000
	s_mov_b64 s[8:9], 0x1400
	s_mov_b64 s[14:15], 0x1800
	s_mov_b64 s[18:19], 0x1c00
	v_lshl_or_b32 v0, v103, 4, v0
	v_readlane_b32 s3, v252, 63
	v_lshl_add_u64 v[60:61], v[54:55], 0, s[4:5]
	v_lshl_add_u64 v[62:63], v[54:55], 0, s[8:9]
	v_lshl_add_u64 v[64:65], v[54:55], 0, s[14:15]
	v_lshl_add_u64 v[66:67], v[54:55], 0, s[18:19]
	v_lshl_add_u64 v[72:73], v[70:71], 0, s[4:5]
	v_lshl_add_u64 v[74:75], v[70:71], 0, s[8:9]
	v_lshl_add_u64 v[76:77], v[70:71], 0, s[14:15]
	v_lshl_add_u64 v[78:79], v[70:71], 0, s[18:19]
	v_lshl_add_u64 v[82:83], s[2:3], 0, v[0:1]
	s_mov_b64 s[2:3], 0
	global_load_dwordx4 v[136:139], v[54:55], off
	global_load_dwordx4 v[140:143], v[54:55], off offset:1024
	global_load_dwordx4 v[144:147], v[54:55], off offset:2048
	global_load_dwordx4 v[148:151], v[54:55], off offset:3072
	global_load_dwordx4 v[152:155], v[60:61], off
	global_load_dwordx4 v[156:159], v[62:63], off
	global_load_dwordx4 v[160:163], v[64:65], off
	global_load_dwordx4 v[164:167], v[66:67], off
	global_load_dwordx4 v[168:171], v[70:71], off
	global_load_dwordx4 v[172:175], v[70:71], off offset:1024
	global_load_dwordx4 v[176:179], v[70:71], off offset:2048
	global_load_dwordx4 v[180:183], v[70:71], off offset:3072
	global_load_dwordx4 v[184:187], v[72:73], off
	global_load_dwordx4 v[188:191], v[74:75], off
	global_load_dwordx4 v[192:195], v[76:77], off
	global_load_dwordx4 v[204:207], v[78:79], off
	s_branch .LBB0_2099

; __device__ __forceinline__ void phase_norm_out(const Params& P, int l, int gw, int NGW, int lane) {
;     ...
;     for (int r = gw; r < MROWS; r += NGW) {
;         f32x4 f[8], x[8];
;         if (r < TP) row_load(F + (size_t)r * DM, lane, f);
;         else { const float* sr = (const float*)(P.ws + WS_SROW) + (size_t)(r - TP) * DM; row_load(sr, lane, f);
; #pragma unroll
;             for (int p = 1; p < 11; ++p) { f32x4 t[8]; row_load(sr + (size_t)p * 128 * DM, lane, t);
; #pragma unroll
;                 for (int j = 0; j < 8; ++j) f[j] = f[j] + t[j]; } }
;         row_load(X1 + (size_t)r * DM, lane, x);
;         __builtin_amdgcn_sched_barrier(0);
;         const float rs = row_rstd(f);
; #pragma unroll
;         for (int j = 0; j < 8; ++j) { const f32x4 gg = *(const f32x4*)(gp + 4 * lane + 256 * j); x[j] = x[j] + f[j] * rs * gg; *(f32x4*)(dst + (size_t)r * DM + 4 * lane + 256 * j) = x[j]; }
.LBB0_2103:
	s_or_b64 exec, exec, s[4:5]
	v_lshlrev_b64 v[116:117], 13, v[84:85]
	v_lshl_add_u64 v[34:35], v[52:53], 0, v[116:117]
	s_movk_i32 s4, 0x1000
	global_load_dwordx4 v[86:89], v[34:35], off
	global_load_dwordx4 v[90:93], v[34:35], off offset:1024
	global_load_dwordx4 v[94:97], v[34:35], off offset:2048
	global_load_dwordx4 v[98:101], v[34:35], off offset:3072
	v_add_co_u32_e32 v34, vcc, s4, v34
	s_nop 1
	v_addc_co_u32_e32 v35, vcc, 0, v35, vcc
	global_load_dwordx4 v[46:49], v[34:35], off
	global_load_dwordx4 v[42:45], v[34:35], off offset:1024
	global_load_dwordx4 v[38:41], v[34:35], off offset:2048
	s_nop 0
	global_load_dwordx4 v[34:37], v[34:35], off offset:3072
	s_waitcnt vmcnt(15)
	v_pk_mul_f32 v[126:127], v[30:31], v[30:31]
	s_waitcnt vmcnt(14)
	v_pk_mul_f32 v[128:129], v[26:27], v[26:27]
	v_pk_mul_f32 v[112:113], v[32:33], v[32:33]
	v_pk_mul_f32 v[114:115], v[28:29], v[28:29]
	v_mov_b32_e32 v130, v126
	v_mov_b32_e32 v131, v128
	v_mov_b32_e32 v128, v127
	v_pk_add_f32 v[126:127], v[130:131], v[128:129]
	v_mov_b32_e32 v128, v112
	v_mov_b32_e32 v129, v114
	v_mov_b32_e32 v114, v113
	v_pk_add_f32 v[112:113], v[128:129], v[114:115]
	s_waitcnt vmcnt(13)
	v_pk_mul_f32 v[122:123], v[24:25], v[24:25]
	v_pk_add_f32 v[112:113], v[126:127], v[112:113]
	v_pk_mul_f32 v[124:125], v[22:23], v[22:23]
	v_pk_add_f32 v[126:127], v[112:113], v[112:113] op_sel_hi:[0,1]
	v_pk_mov_b32 v[128:129], v[124:125], v[122:123] op_sel:[1,0]
	v_mov_b32_e32 v125, v123
	s_waitcnt vmcnt(12)
	v_mul_f32_e32 v8, v18, v18
	v_pk_add_f32 v[122:123], v[128:129], v[124:125]
	v_pk_fma_f32 v[124:125], v[18:19], v[18:19], v[8:9] op_sel_hi:[1,1,0]
	v_mul_f32_e32 v8, v20, v20
	v_pk_add_f32 v[122:123], v[122:123], v[122:123] op_sel_hi:[0,1]
	v_pk_fma_f32 v[128:129], v[20:21], v[20:21], v[8:9] op_sel_hi:[1,1,0]
	s_waitcnt vmcnt(11)
	v_mul_f32_e32 v124, v14, v14
	v_mul_f32_e32 v128, v15, v15
	v_mul_f32_e32 v122, v16, v16
	v_mul_f32_e32 v126, v17, v17
	s_waitcnt vmcnt(10)
	v_pk_mul_f32 v[118:119], v[12:13], v[12:13]
	v_pk_mul_f32 v[120:121], v[10:11], v[10:11]
	v_pk_add_f32 v[124:125], v[124:125], v[128:129]
	v_pk_add_f32 v[122:123], v[122:123], v[126:127]
	s_waitcnt vmcnt(9)
	v_mul_f32_e32 v8, v4, v4
	v_pk_add_f32 v[122:123], v[124:125], v[122:123]
	v_pk_mov_b32 v[124:125], v[120:121], v[118:119] op_sel:[1,0]
	v_mov_b32_e32 v121, v119
	v_pk_add_f32 v[118:119], v[124:125], v[120:121]
	v_pk_fma_f32 v[120:121], v[4:5], v[4:5], v[8:9] op_sel_hi:[1,1,0]
	v_mul_f32_e32 v8, v6, v6
	v_pk_add_f32 v[122:123], v[122:123], v[122:123] op_sel_hi:[0,1]
	v_pk_add_f32 v[118:119], v[118:119], v[118:119] op_sel_hi:[0,1]
	v_pk_fma_f32 v[124:125], v[6:7], v[6:7], v[8:9] op_sel_hi:[1,1,0]
	s_waitcnt vmcnt(8)
	v_mul_f32_e32 v120, v0, v0
	v_mul_f32_e32 v124, v1, v1
	v_mul_f32_e32 v118, v2, v2
	v_mul_f32_e32 v122, v3, v3
	v_pk_add_f32 v[120:121], v[120:121], v[124:125]
	v_pk_add_f32 v[118:119], v[118:119], v[122:123]
	v_lshl_add_u64 v[116:117], v[56:57], 0, v[116:117]
	v_pk_add_f32 v[118:119], v[120:121], v[118:119]
	s_nop 0
	v_add_f32_e32 v8, v118, v119
	ds_bpermute_b32 v51, v105, v8
	s_waitcnt lgkmcnt(0)
	v_add_f32_e32 v8, v8, v51
	ds_bpermute_b32 v51, v106, v8
	s_waitcnt lgkmcnt(0)
	v_add_f32_e32 v8, v8, v51
	ds_bpermute_b32 v51, v107, v8
	s_waitcnt lgkmcnt(0)
	v_add_f32_e32 v8, v8, v51
	ds_bpermute_b32 v51, v108, v8
	s_waitcnt lgkmcnt(0)
	v_add_f32_e32 v8, v8, v51
	ds_bpermute_b32 v51, v109, v8
	s_waitcnt lgkmcnt(0)
	v_add_f32_e32 v8, v8, v51
	ds_bpermute_b32 v51, v110, v8
	s_waitcnt lgkmcnt(0)
	v_add_f32_e32 v8, v8, v51
	v_fmamk_f32 v8, v8, 0x3a000000, v240
	v_mul_f32_e32 v51, 0x4b800000, v8
	v_cmp_gt_f32_e32 vcc, s72, v8
	s_nop 1
	v_cndmask_b32_e32 v8, v8, v51, vcc
	v_rsq_f32_e32 v8, v8
	s_nop 0
	v_mul_f32_e32 v51, 0x45800000, v8
	v_cndmask_b32_e32 v8, v8, v51, vcc
	v_pk_mul_f32 v[30:31], v[30:31], v[8:9] op_sel_hi:[1,0]
	v_pk_mul_f32 v[32:33], v[32:33], v[8:9] op_sel_hi:[1,0]
	s_waitcnt vmcnt(0)
	v_pk_fma_f32 v[30:31], v[136:137], v[30:31], v[86:87]
	v_pk_fma_f32 v[32:33], v[138:139], v[32:33], v[88:89]
	global_store_dwordx4 v[116:117], v[30:33], off
	v_pk_mul_f32 v[28:29], v[28:29], v[8:9] op_sel_hi:[1,0]
	v_pk_mul_f32 v[26:27], v[26:27], v[8:9] op_sel_hi:[1,0]
	v_pk_mul_f32 v[24:25], v[24:25], v[8:9] op_sel_hi:[1,0]
	v_pk_mul_f32 v[22:23], v[22:23], v[8:9] op_sel_hi:[1,0]
	v_pk_mul_f32 v[20:21], v[20:21], v[8:9] op_sel_hi:[1,0]
	v_pk_mul_f32 v[18:19], v[18:19], v[8:9] op_sel_hi:[1,0]
	v_pk_mul_f32 v[16:17], v[16:17], v[8:9] op_sel_hi:[1,0]
	v_pk_mul_f32 v[14:15], v[14:15], v[8:9] op_sel_hi:[1,0]
	v_pk_mul_f32 v[12:13], v[12:13], v[8:9] op_sel_hi:[1,0]
	v_pk_mul_f32 v[10:11], v[10:11], v[8:9] op_sel_hi:[1,0]
	v_pk_mul_f32 v[6:7], v[6:7], v[8:9] op_sel_hi:[1,0]
	v_pk_mul_f32 v[4:5], v[4:5], v[8:9] op_sel_hi:[1,0]
	v_pk_mul_f32 v[2:3], v[2:3], v[8:9] op_sel_hi:[1,0]
	v_pk_mul_f32 v[0:1], v[0:1], v[8:9] op_sel_hi:[1,0]
	v_pk_fma_f32 v[26:27], v[140:141], v[26:27], v[90:91]
	v_pk_fma_f32 v[28:29], v[142:143], v[28:29], v[92:93]
	global_store_dwordx4 v[116:117], v[26:29], off offset:1024
	v_add_co_u32_e32 v90, vcc, s4, v116
	v_pk_fma_f32 v[22:23], v[144:145], v[22:23], v[94:95]
	v_pk_fma_f32 v[24:25], v[146:147], v[24:25], v[96:97]
	global_store_dwordx4 v[116:117], v[22:25], off offset:2048
	v_addc_co_u32_e32 v91, vcc, 0, v117, vcc
	s_and_b64 vcc, exec, s[26:27]
	v_pk_fma_f32 v[18:19], v[148:149], v[18:19], v[98:99]
	v_pk_fma_f32 v[20:21], v[150:151], v[20:21], v[100:101]
	global_store_dwordx4 v[116:117], v[18:21], off offset:3072
	v_pk_fma_f32 v[14:15], v[152:153], v[14:15], v[46:47]
	v_pk_fma_f32 v[16:17], v[154:155], v[16:17], v[48:49]
	global_store_dwordx4 v[90:91], v[14:17], off
	v_pk_fma_f32 v[10:11], v[156:157], v[10:11], v[42:43]
	v_pk_fma_f32 v[12:13], v[158:159], v[12:13], v[44:45]
	global_store_dwordx4 v[90:91], v[10:13], off offset:1024
	v_pk_fma_f32 v[4:5], v[4:5], v[160:161], v[38:39]
	v_pk_fma_f32 v[6:7], v[6:7], v[162:163], v[40:41]
	global_store_dwordx4 v[90:91], v[4:7], off offset:2048
	v_pk_fma_f32 v[0:1], v[0:1], v[164:165], v[34:35]
	v_pk_fma_f32 v[2:3], v[2:3], v[166:167], v[36:37]
	global_store_dwordx4 v[90:91], v[0:3], off offset:3072
	s_cbranch_vccnz .LBB0_2098
; __device__ __forceinline__ unsigned pk2(float lo, float hi) { unsigned r; asm("v_cvt_pk_bf16_f32 %0, %1, %2" : "=v"(r) : "v"(lo), "v"(hi)); return r; }
; __device__ __forceinline__ float row_rstd(const f32x4 (&v)[8]) {
;     float s = 0.f;
; #pragma unroll
;     for (int j = 0; j < 8; ++j) s += (v[j][0] * v[j][0] + v[j][1] * v[j][1]) + (v[j][2] * v[j][2] + v[j][3] * v[j][3]);
;     return rsqrtf(wave_sum(s) * (1.f / DM) + EPSN);
; }
; __device__ __forceinline__ void row_store_bf16(bf16_t* o, int lane, const f32x4 (&v)[8], float rstd, const float* g) {
; #pragma unroll
;     for (int j = 0; j < 8; ++j) { const f32x4 gg = *(const f32x4*)(g + 4 * lane + 256 * j);
;         u32x2 w; w.x = pk2(v[j][0] * rstd * gg[0], v[j][1] * rstd * gg[1]); w.y = pk2(v[j][2] * rstd * gg[2], v[j][3] * rstd * gg[3]);
;         *(u32x2*)(o + 4 * lane + 256 * j) = w; }
; }
; __device__ __forceinline__ void phase_norm_out(const Params& P, int l, int gw, int NGW, int lane) {
;     ...
;         if (l == 0) { const float rs2 = row_rstd(x); row_store_bf16(H + (size_t)r * DM, lane, x, rs2, P.g_mix_pre + DM); }
	v_mov_b32_e32 v38, v31
	v_mov_b32_e32 v39, v27
	v_mov_b32_e32 v36, v30
	v_mov_b32_e32 v37, v26
	v_pk_mul_f32 v[38:39], v[38:39], v[38:39]
	v_mov_b32_e32 v40, v33
	v_mov_b32_e32 v41, v29
	v_pk_fma_f32 v[36:37], v[36:37], v[36:37], v[38:39]
	v_mov_b32_e32 v38, v32
	v_mov_b32_e32 v39, v28
	v_pk_mul_f32 v[40:41], v[40:41], v[40:41]
	v_mul_f32_e32 v8, v18, v18
	v_pk_fma_f32 v[38:39], v[38:39], v[38:39], v[40:41]
	v_pk_mul_f32 v[40:41], v[22:23], v[22:23]
	v_pk_add_f32 v[36:37], v[36:37], v[38:39]
	v_pk_mul_f32 v[38:39], v[24:25], v[24:25]
	v_pk_add_f32 v[36:37], v[36:37], v[36:37] op_sel_hi:[0,1]
	v_pk_mov_b32 v[42:43], v[40:41], v[38:39] op_sel:[1,0]
	v_mov_b32_e32 v41, v39
	v_pk_add_f32 v[38:39], v[42:43], v[40:41]
	v_pk_fma_f32 v[40:41], v[18:19], v[18:19], v[8:9] op_sel_hi:[1,1,0]
	v_mul_f32_e32 v8, v20, v20
	v_pk_add_f32 v[38:39], v[38:39], v[38:39] op_sel_hi:[0,1]
	v_pk_fma_f32 v[42:43], v[20:21], v[20:21], v[8:9] op_sel_hi:[1,1,0]
	v_mul_f32_e32 v40, v14, v14
	v_mul_f32_e32 v42, v15, v15
	v_mul_f32_e32 v38, v16, v16
	v_mul_f32_e32 v36, v17, v17
	v_pk_add_f32 v[40:41], v[40:41], v[42:43]
	v_pk_add_f32 v[36:37], v[38:39], v[36:37]
	v_pk_mul_f32 v[38:39], v[12:13], v[12:13]
	v_pk_add_f32 v[36:37], v[40:41], v[36:37]
	v_pk_mul_f32 v[40:41], v[10:11], v[10:11]
	v_mul_f32_e32 v8, v4, v4
	v_pk_mov_b32 v[42:43], v[40:41], v[38:39] op_sel:[1,0]
	v_mov_b32_e32 v41, v39
	v_pk_add_f32 v[38:39], v[42:43], v[40:41]
	v_pk_fma_f32 v[40:41], v[4:5], v[4:5], v[8:9] op_sel_hi:[1,1,0]
	v_mul_f32_e32 v8, v6, v6
	v_pk_add_f32 v[36:37], v[36:37], v[36:37] op_sel_hi:[0,1]
	v_pk_add_f32 v[38:39], v[38:39], v[38:39] op_sel_hi:[0,1]
	v_pk_fma_f32 v[42:43], v[6:7], v[6:7], v[8:9] op_sel_hi:[1,1,0]
	v_mul_f32_e32 v40, v0, v0
	v_mul_f32_e32 v42, v1, v1
	v_mul_f32_e32 v38, v2, v2
	v_mul_f32_e32 v36, v3, v3
	v_pk_add_f32 v[40:41], v[40:41], v[42:43]
	v_pk_add_f32 v[36:37], v[38:39], v[36:37]
	v_lshlrev_b64 v[34:35], 11, v[84:85]
	v_pk_add_f32 v[36:37], v[40:41], v[36:37]
	v_lshl_add_u64 v[34:35], v[34:35], 1, v[58:59]
	v_add_f32_e32 v8, v36, v37
	ds_bpermute_b32 v36, v105, v8
	s_waitcnt lgkmcnt(0)
	v_add_f32_e32 v8, v8, v36
	ds_bpermute_b32 v36, v106, v8
	s_waitcnt lgkmcnt(0)
	v_add_f32_e32 v8, v8, v36
	ds_bpermute_b32 v36, v107, v8
	s_waitcnt lgkmcnt(0)
	v_add_f32_e32 v8, v8, v36
	ds_bpermute_b32 v36, v108, v8
	s_waitcnt lgkmcnt(0)
	v_add_f32_e32 v8, v8, v36
	ds_bpermute_b32 v36, v109, v8
	s_waitcnt lgkmcnt(0)
	v_add_f32_e32 v8, v8, v36
	ds_bpermute_b32 v36, v110, v8
	s_waitcnt lgkmcnt(0)
	v_add_f32_e32 v8, v8, v36
	v_fmamk_f32 v8, v8, 0x3a000000, v240
	v_cmp_gt_f32_e32 vcc, s72, v8
	v_mul_f32_e32 v36, 0x4b800000, v8
	s_nop 0
	v_cndmask_b32_e32 v8, v8, v36, vcc
	v_rsq_f32_e32 v8, v8
	s_nop 0
	v_mul_f32_e32 v36, 0x45800000, v8
	v_cndmask_b32_e32 v8, v8, v36, vcc
	v_mul_f32_e32 v30, v30, v8
	v_mul_f32_e32 v31, v31, v8
	v_mul_f32_e32 v26, v26, v8
	v_mul_f32_e32 v27, v27, v8
	v_mul_f32_e32 v22, v22, v8
	v_mul_f32_e32 v23, v23, v8
	v_mul_f32_e32 v18, v18, v8
	v_mul_f32_e32 v19, v19, v8
	v_mul_f32_e32 v14, v14, v8
	v_mul_f32_e32 v15, v15, v8
	v_mul_f32_e32 v10, v10, v8
	v_mul_f32_e32 v11, v11, v8
	v_mul_f32_e32 v4, v4, v8
	v_mul_f32_e32 v5, v5, v8
	v_mul_f32_e32 v0, v0, v8
	v_mul_f32_e32 v1, v1, v8
	v_mul_f32_e32 v30, v168, v30
	v_mul_f32_e32 v31, v169, v31
	v_cvt_pk_bf16_f32 v30, v30, v31
	v_mul_f32_e32 v31, v32, v8
	v_mul_f32_e32 v31, v170, v31
	v_mul_f32_e32 v32, v33, v8
	v_mul_f32_e32 v32, v171, v32
	v_cvt_pk_bf16_f32 v31, v31, v32
	global_store_dwordx2 v[34:35], v[30:31], off
	v_mul_f32_e32 v26, v172, v26
	v_mul_f32_e32 v27, v173, v27
	v_cvt_pk_bf16_f32 v26, v26, v27
	v_mul_f32_e32 v27, v28, v8
	v_mul_f32_e32 v27, v174, v27
	v_mul_f32_e32 v28, v29, v8
	v_mul_f32_e32 v28, v175, v28
	v_cvt_pk_bf16_f32 v27, v27, v28
	global_store_dwordx2 v[34:35], v[26:27], off offset:512
	v_mul_f32_e32 v22, v176, v22
	v_mul_f32_e32 v23, v177, v23
	v_cvt_pk_bf16_f32 v22, v22, v23
	v_mul_f32_e32 v23, v24, v8
	v_mul_f32_e32 v23, v178, v23
	v_mul_f32_e32 v24, v25, v8
	v_mul_f32_e32 v24, v179, v24
	v_cvt_pk_bf16_f32 v23, v23, v24
	global_store_dwordx2 v[34:35], v[22:23], off offset:1024
	v_mul_f32_e32 v18, v18, v180
	v_mul_f32_e32 v19, v19, v181
	v_cvt_pk_bf16_f32 v18, v18, v19
	v_mul_f32_e32 v19, v20, v8
	v_mul_f32_e32 v19, v19, v182
	v_mul_f32_e32 v20, v21, v8
	v_mul_f32_e32 v20, v20, v183
	v_cvt_pk_bf16_f32 v19, v19, v20
	global_store_dwordx2 v[34:35], v[18:19], off offset:1536
	v_mul_f32_e32 v14, v14, v184
	v_mul_f32_e32 v15, v15, v185
	v_cvt_pk_bf16_f32 v14, v14, v15
	v_mul_f32_e32 v15, v16, v8
	v_mul_f32_e32 v15, v15, v186
	v_mul_f32_e32 v16, v17, v8
	v_mul_f32_e32 v16, v16, v187
	v_cvt_pk_bf16_f32 v15, v15, v16
	global_store_dwordx2 v[34:35], v[14:15], off offset:2048
	v_mul_f32_e32 v10, v10, v188
	v_mul_f32_e32 v11, v11, v189
	v_cvt_pk_bf16_f32 v10, v10, v11
	v_mul_f32_e32 v11, v12, v8
	v_mul_f32_e32 v11, v11, v190
	v_mul_f32_e32 v12, v13, v8
	v_mul_f32_e32 v12, v12, v191
	v_cvt_pk_bf16_f32 v11, v11, v12
	global_store_dwordx2 v[34:35], v[10:11], off offset:2560
	v_mul_f32_e32 v4, v4, v192
	v_mul_f32_e32 v5, v5, v193
	v_cvt_pk_bf16_f32 v4, v4, v5
	v_mul_f32_e32 v5, v6, v8
	v_mul_f32_e32 v5, v5, v194
	v_mul_f32_e32 v6, v7, v8
	v_mul_f32_e32 v6, v6, v195
	v_cvt_pk_bf16_f32 v5, v5, v6
	global_store_dwordx2 v[34:35], v[4:5], off offset:3072
	v_mul_f32_e32 v0, v0, v204
	v_mul_f32_e32 v1, v1, v205
	v_cvt_pk_bf16_f32 v0, v0, v1
	v_mul_f32_e32 v1, v2, v8
	v_mul_f32_e32 v1, v1, v206
	v_mul_f32_e32 v2, v3, v8
	v_mul_f32_e32 v2, v2, v207
	v_cvt_pk_bf16_f32 v1, v1, v2
	global_store_dwordx2 v[34:35], v[0:1], off offset:3584
	s_branch .LBB0_2098
